# attention: static priority split, OLDER half (waves 0-3) s_setprio 1, younger 0
# baseline (speedup 1.0000x reference)
.LBB0_96:
	s_lshl_b32 s23, s38, 11
	s_and_b32 s22, s39, s37
	s_addk_i32 s23, 0x2000
	s_lshl_b32 s24, s38, 8
	s_and_b64 s[12:13], s[12:13], exec
	s_cselect_b32 s24, s23, s24
	s_lshl_b32 s25, s22, 7
	s_waitcnt lgkmcnt(0)
	s_add_u32 s12, s4, s29
	s_addc_u32 s13, s5, 0
	s_add_u32 s22, s12, 0x629c000
	s_addc_u32 s23, s13, 0
	global_load_dword v113, v192, s[12:13]
	global_load_dword v112, v133, s[22:23] offset:8
	s_mov_b64 s[12:13], s[0:1]
	s_load_dwordx2 s[12:13], s[12:13], 0x68
	v_lshlrev_b32_e32 v0, 2, v40
	v_and_b32_e32 v0, 60, v0
	v_ashrrev_i32_e32 v13, 4, v40
	v_lshl_or_b32 v12, s35, 6, v0
	v_add_u32_e32 v29, s25, v13
	v_lshlrev_b32_e32 v0, 2, v12
	v_lshlrev_b32_e32 v132, 1, v12
	v_add_u32_e32 v18, s24, v29
	v_ashrrev_i32_e32 v19, 31, v18
	s_waitcnt lgkmcnt(0)
	s_add_u32 s12, s12, s6
	s_addc_u32 s13, s13, s7
	global_load_dwordx4 v[8:11], v0, s[12:13]
	global_load_dwordx4 v[4:7], v0, s[12:13] offset:1024
	s_nop 0
	global_load_dwordx4 v[0:3], v0, s[12:13] offset:2048
	v_lshl_add_u64 v[14:15], s[4:5], 0, v[132:133]
	v_lshlrev_b64 v[20:21], 9, v[18:19]
	s_mov_b64 s[12:13], 0xdea4400
	v_lshl_add_u64 v[16:17], v[14:15], 0, s[12:13]
	s_mov_b64 s[12:13], 0xe6a4400
	v_lshl_add_u64 v[22:23], v[14:15], 0, s[12:13]
	s_mov_b64 s[12:13], 0xd6a4400
	v_lshl_add_u64 v[24:25], v[14:15], 0, s[12:13]
	v_lshl_add_u64 v[16:17], v[16:17], 0, v[20:21]
	v_lshl_add_u64 v[22:23], v[22:23], 0, v[20:21]
	v_lshl_add_u64 v[24:25], v[24:25], 0, v[20:21]
	global_load_dwordx2 v[44:45], v[16:17], off offset:-512
	global_load_dwordx2 v[46:47], v[16:17], off
	global_load_dwordx2 v[48:49], v[16:17], off offset:512
	global_load_dwordx2 v[50:51], v[22:23], off offset:-512
	global_load_dwordx2 v[52:53], v[22:23], off
	global_load_dwordx2 v[54:55], v[22:23], off offset:512
	global_load_dwordx2 v[56:57], v[24:25], off
	v_lshl_add_u64 v[16:17], v[16:17], 0, s[76:77]
	v_lshl_add_u64 v[22:23], v[22:23], 0, s[76:77]
	v_lshl_add_u64 v[24:25], v[24:25], 0, s[76:77]
	global_load_dwordx2 v[58:59], v[16:17], off offset:-512
	global_load_dwordx2 v[60:61], v[16:17], off
	global_load_dwordx2 v[62:63], v[16:17], off offset:512
	global_load_dwordx2 v[64:65], v[22:23], off offset:-512
	global_load_dwordx2 v[66:67], v[22:23], off
	global_load_dwordx2 v[68:69], v[22:23], off offset:512
	global_load_dwordx2 v[70:71], v[24:25], off
	v_lshl_add_u64 v[16:17], v[16:17], 0, s[76:77]
	v_lshl_add_u64 v[22:23], v[22:23], 0, s[76:77]
	v_lshl_add_u64 v[24:25], v[24:25], 0, s[76:77]
	global_load_dwordx2 v[72:73], v[16:17], off offset:-512
	global_load_dwordx2 v[74:75], v[16:17], off
	global_load_dwordx2 v[76:77], v[16:17], off offset:512
	global_load_dwordx2 v[78:79], v[22:23], off offset:-512
	global_load_dwordx2 v[80:81], v[22:23], off
	global_load_dwordx2 v[82:83], v[22:23], off offset:512
	global_load_dwordx2 v[84:85], v[24:25], off
	v_lshl_add_u64 v[16:17], v[16:17], 0, s[76:77]
	v_lshl_add_u64 v[22:23], v[22:23], 0, s[76:77]
	v_lshl_add_u64 v[24:25], v[24:25], 0, s[76:77]
	global_load_dwordx2 v[86:87], v[16:17], off offset:-512
	global_load_dwordx2 v[88:89], v[16:17], off
	global_load_dwordx2 v[90:91], v[16:17], off offset:512
	global_load_dwordx2 v[92:93], v[22:23], off offset:-512
	global_load_dwordx2 v[94:95], v[22:23], off
	global_load_dwordx2 v[96:97], v[22:23], off offset:512
	global_load_dwordx2 v[98:99], v[24:25], off
	s_add_u32 s12, s4, 0xfea4400
	s_addc_u32 s13, s5, 0
	v_mov_b64_e32 v[26:27], s[12:13]
	v_mad_i64_i32 v[26:27], s[22:23], v18, s96, v[26:27]
	v_lshl_add_u64 v[26:27], v[26:27], 0, v[132:133]
	s_mov_b64 s[12:13], 0x14000
	v_add_u32_e32 v28, 0x60, v29
	s_waitcnt vmcnt(21)
	v_lshlrev_b32_e32 v100, 16, v44
	v_and_b32_e32 v101, 0xffff0000, v44
	v_lshlrev_b32_e32 v102, 16, v50
	v_and_b32_e32 v103, 0xffff0000, v50
	v_lshlrev_b32_e32 v104, 16, v45
	v_and_b32_e32 v105, 0xffff0000, v45
	v_lshlrev_b32_e32 v106, 16, v51
	v_and_b32_e32 v107, 0xffff0000, v51
	v_pk_mul_f32 v[30:31], v[100:101], v[102:103]
	v_pk_mul_f32 v[32:33], v[104:105], v[106:107]
	v_lshlrev_b32_e32 v100, 16, v46
	v_and_b32_e32 v101, 0xffff0000, v46
	v_lshlrev_b32_e32 v102, 16, v52
	v_and_b32_e32 v103, 0xffff0000, v52
	v_lshlrev_b32_e32 v104, 16, v47
	v_and_b32_e32 v105, 0xffff0000, v47
	v_lshlrev_b32_e32 v106, 16, v53
	v_and_b32_e32 v107, 0xffff0000, v53
	v_pk_mul_f32 v[34:35], v[100:101], v[102:103]
	v_pk_mul_f32 v[36:37], v[104:105], v[106:107]
	v_lshlrev_b32_e32 v100, 16, v48
	v_and_b32_e32 v101, 0xffff0000, v48
	v_lshlrev_b32_e32 v102, 16, v54
	v_and_b32_e32 v103, 0xffff0000, v54
	v_lshlrev_b32_e32 v104, 16, v49
	v_and_b32_e32 v105, 0xffff0000, v49
	v_lshlrev_b32_e32 v106, 16, v55
	v_and_b32_e32 v107, 0xffff0000, v55
	v_pk_mul_f32 v[108:109], v[100:101], v[102:103]
	v_pk_mul_f32 v[110:111], v[104:105], v[106:107]
	v_cmp_lt_i32_e32 vcc, 0, v29
	s_nop 1
	v_cndmask_b32_e32 v30, 0, v30, vcc
	v_cndmask_b32_e32 v31, 0, v31, vcc
	v_cndmask_b32_e32 v32, 0, v32, vcc
	v_cndmask_b32_e32 v33, 0, v33, vcc
	v_pk_mul_f32 v[32:33], v[10:11], v[32:33]
	v_pk_mul_f32 v[30:31], v[8:9], v[30:31]
	v_pk_fma_f32 v[32:33], v[6:7], v[36:37], v[32:33]
	v_pk_fma_f32 v[30:31], v[4:5], v[34:35], v[30:31]
	v_pk_fma_f32 v[30:31], v[0:1], v[108:109], v[30:31]
	v_pk_fma_f32 v[32:33], v[2:3], v[110:111], v[32:33]
	v_lshlrev_b32_e32 v100, 16, v56
	v_and_b32_e32 v101, 0xffff0000, v56
	v_lshlrev_b32_e32 v102, 16, v57
	v_and_b32_e32 v103, 0xffff0000, v57
	v_pk_mul_f32 v[32:33], v[32:33], v[102:103]
	v_pk_mul_f32 v[30:31], v[30:31], v[100:101]
	v_cvt_pk_bf16_f32 v30, v30, v31
	v_cvt_pk_bf16_f32 v31, v32, v33
	global_store_dwordx2 v[26:27], v[30:31], off offset:1024
	v_lshl_add_u64 v[26:27], v[26:27], 0, s[12:13]
	s_waitcnt vmcnt(14)
	v_lshlrev_b32_e32 v100, 16, v58
	v_and_b32_e32 v101, 0xffff0000, v58
	v_lshlrev_b32_e32 v102, 16, v64
	v_and_b32_e32 v103, 0xffff0000, v64
	v_lshlrev_b32_e32 v104, 16, v59
	v_and_b32_e32 v105, 0xffff0000, v59
	v_lshlrev_b32_e32 v106, 16, v65
	v_and_b32_e32 v107, 0xffff0000, v65
	v_pk_mul_f32 v[30:31], v[100:101], v[102:103]
	v_pk_mul_f32 v[32:33], v[104:105], v[106:107]
	v_lshlrev_b32_e32 v100, 16, v60
	v_and_b32_e32 v101, 0xffff0000, v60
	v_lshlrev_b32_e32 v102, 16, v66
	v_and_b32_e32 v103, 0xffff0000, v66
	v_lshlrev_b32_e32 v104, 16, v61
	v_and_b32_e32 v105, 0xffff0000, v61
	v_lshlrev_b32_e32 v106, 16, v67
	v_and_b32_e32 v107, 0xffff0000, v67
	v_pk_mul_f32 v[34:35], v[100:101], v[102:103]
	v_pk_mul_f32 v[36:37], v[104:105], v[106:107]
	v_lshlrev_b32_e32 v100, 16, v62
	v_and_b32_e32 v101, 0xffff0000, v62
	v_lshlrev_b32_e32 v102, 16, v68
	v_and_b32_e32 v103, 0xffff0000, v68
	v_lshlrev_b32_e32 v104, 16, v63
	v_and_b32_e32 v105, 0xffff0000, v63
	v_lshlrev_b32_e32 v106, 16, v69
	v_and_b32_e32 v107, 0xffff0000, v69
	v_pk_mul_f32 v[108:109], v[100:101], v[102:103]
	v_pk_mul_f32 v[110:111], v[104:105], v[106:107]
	v_pk_mul_f32 v[32:33], v[10:11], v[32:33]
	v_pk_mul_f32 v[30:31], v[8:9], v[30:31]
	v_pk_fma_f32 v[32:33], v[6:7], v[36:37], v[32:33]
	v_pk_fma_f32 v[30:31], v[4:5], v[34:35], v[30:31]
	v_pk_fma_f32 v[30:31], v[0:1], v[108:109], v[30:31]
	v_pk_fma_f32 v[32:33], v[2:3], v[110:111], v[32:33]
	v_lshlrev_b32_e32 v100, 16, v70
	v_and_b32_e32 v101, 0xffff0000, v70
	v_lshlrev_b32_e32 v102, 16, v71
	v_and_b32_e32 v103, 0xffff0000, v71
	v_pk_mul_f32 v[32:33], v[32:33], v[102:103]
	v_pk_mul_f32 v[30:31], v[30:31], v[100:101]
	v_cvt_pk_bf16_f32 v30, v30, v31
	v_cvt_pk_bf16_f32 v31, v32, v33
	global_store_dwordx2 v[26:27], v[30:31], off offset:1024
	v_lshl_add_u64 v[26:27], v[26:27], 0, s[12:13]
	s_waitcnt vmcnt(7)
	v_lshlrev_b32_e32 v100, 16, v72
	v_and_b32_e32 v101, 0xffff0000, v72
	v_lshlrev_b32_e32 v102, 16, v78
	v_and_b32_e32 v103, 0xffff0000, v78
	v_lshlrev_b32_e32 v104, 16, v73
	v_and_b32_e32 v105, 0xffff0000, v73
	v_lshlrev_b32_e32 v106, 16, v79
	v_and_b32_e32 v107, 0xffff0000, v79
	v_pk_mul_f32 v[30:31], v[100:101], v[102:103]
	v_pk_mul_f32 v[32:33], v[104:105], v[106:107]
	v_lshlrev_b32_e32 v100, 16, v74
	v_and_b32_e32 v101, 0xffff0000, v74
	v_lshlrev_b32_e32 v102, 16, v80
	v_and_b32_e32 v103, 0xffff0000, v80
	v_lshlrev_b32_e32 v104, 16, v75
	v_and_b32_e32 v105, 0xffff0000, v75
	v_lshlrev_b32_e32 v106, 16, v81
	v_and_b32_e32 v107, 0xffff0000, v81
	v_pk_mul_f32 v[34:35], v[100:101], v[102:103]
	v_pk_mul_f32 v[36:37], v[104:105], v[106:107]
	v_lshlrev_b32_e32 v100, 16, v76
	v_and_b32_e32 v101, 0xffff0000, v76
	v_lshlrev_b32_e32 v102, 16, v82
	v_and_b32_e32 v103, 0xffff0000, v82
	v_lshlrev_b32_e32 v104, 16, v77
	v_and_b32_e32 v105, 0xffff0000, v77
	v_lshlrev_b32_e32 v106, 16, v83
	v_and_b32_e32 v107, 0xffff0000, v83
	v_pk_mul_f32 v[108:109], v[100:101], v[102:103]
	v_pk_mul_f32 v[110:111], v[104:105], v[106:107]
	v_pk_mul_f32 v[32:33], v[10:11], v[32:33]
	v_pk_mul_f32 v[30:31], v[8:9], v[30:31]
	v_pk_fma_f32 v[32:33], v[6:7], v[36:37], v[32:33]
	v_pk_fma_f32 v[30:31], v[4:5], v[34:35], v[30:31]
	v_pk_fma_f32 v[30:31], v[0:1], v[108:109], v[30:31]
	v_pk_fma_f32 v[32:33], v[2:3], v[110:111], v[32:33]
	v_lshlrev_b32_e32 v100, 16, v84
	v_and_b32_e32 v101, 0xffff0000, v84
	v_lshlrev_b32_e32 v102, 16, v85
	v_and_b32_e32 v103, 0xffff0000, v85
	v_pk_mul_f32 v[32:33], v[32:33], v[102:103]
	v_pk_mul_f32 v[30:31], v[30:31], v[100:101]
	v_cvt_pk_bf16_f32 v30, v30, v31
	v_cvt_pk_bf16_f32 v31, v32, v33
	global_store_dwordx2 v[26:27], v[30:31], off offset:1024
	v_lshl_add_u64 v[26:27], v[26:27], 0, s[12:13]
	s_waitcnt vmcnt(0)
	v_lshlrev_b32_e32 v100, 16, v86
	v_and_b32_e32 v101, 0xffff0000, v86
	v_lshlrev_b32_e32 v102, 16, v92
	v_and_b32_e32 v103, 0xffff0000, v92
	v_lshlrev_b32_e32 v104, 16, v87
	v_and_b32_e32 v105, 0xffff0000, v87
	v_lshlrev_b32_e32 v106, 16, v93
	v_and_b32_e32 v107, 0xffff0000, v93
	v_pk_mul_f32 v[30:31], v[100:101], v[102:103]
	v_pk_mul_f32 v[32:33], v[104:105], v[106:107]
	v_lshlrev_b32_e32 v100, 16, v88
	v_and_b32_e32 v101, 0xffff0000, v88
	v_lshlrev_b32_e32 v102, 16, v94
	v_and_b32_e32 v103, 0xffff0000, v94
	v_lshlrev_b32_e32 v104, 16, v89
	v_and_b32_e32 v105, 0xffff0000, v89
	v_lshlrev_b32_e32 v106, 16, v95
	v_and_b32_e32 v107, 0xffff0000, v95
	v_pk_mul_f32 v[34:35], v[100:101], v[102:103]
	v_pk_mul_f32 v[36:37], v[104:105], v[106:107]
	v_lshlrev_b32_e32 v100, 16, v90
	v_and_b32_e32 v101, 0xffff0000, v90
	v_lshlrev_b32_e32 v102, 16, v96
	v_and_b32_e32 v103, 0xffff0000, v96
	v_lshlrev_b32_e32 v104, 16, v91
	v_and_b32_e32 v105, 0xffff0000, v91
	v_lshlrev_b32_e32 v106, 16, v97
	v_and_b32_e32 v107, 0xffff0000, v97
	v_pk_mul_f32 v[108:109], v[100:101], v[102:103]
	v_pk_mul_f32 v[110:111], v[104:105], v[106:107]
	v_cmp_gt_i32_e32 vcc, s36, v28
	s_nop 1
	v_cndmask_b32_e32 v108, 0, v108, vcc
	v_cndmask_b32_e32 v109, 0, v109, vcc
	v_cndmask_b32_e32 v110, 0, v110, vcc
	v_cndmask_b32_e32 v111, 0, v111, vcc
	v_pk_mul_f32 v[32:33], v[10:11], v[32:33]
	v_pk_mul_f32 v[30:31], v[8:9], v[30:31]
	v_pk_fma_f32 v[32:33], v[6:7], v[36:37], v[32:33]
	v_pk_fma_f32 v[30:31], v[4:5], v[34:35], v[30:31]
	v_pk_fma_f32 v[30:31], v[0:1], v[108:109], v[30:31]
	v_pk_fma_f32 v[32:33], v[2:3], v[110:111], v[32:33]
	v_lshlrev_b32_e32 v100, 16, v98
	v_and_b32_e32 v101, 0xffff0000, v98
	v_lshlrev_b32_e32 v102, 16, v99
	v_and_b32_e32 v103, 0xffff0000, v99
	v_pk_mul_f32 v[32:33], v[32:33], v[102:103]
	v_pk_mul_f32 v[30:31], v[30:31], v[100:101]
	v_cvt_pk_bf16_f32 v30, v30, v31
	v_cvt_pk_bf16_f32 v31, v32, v33
	global_store_dwordx2 v[26:27], v[30:31], off offset:1024
	s_add_u32 s12, s4, 0xfea4400
	s_addc_u32 s13, s5, 0
	v_ashrrev_i32_e32 v42, 6, v40
	v_cmp_lt_i32_e32 vcc, 3, v42
	s_nop 0
	v_readfirstlane_b32 s22, v42
	s_cmp_gt_i32 s22, 3
	s_cbranch_scc0 .Lprio_young
	s_setprio 0
	s_branch .Lprio_done
